# attention loop: shuffle address and V^T read bases hoisted, on top of the softmax/PV priority toggle
# speedup vs baseline: 1.0041x; 1.0035x over previous
.LBB0_376:
	s_setprio 0
	s_or_b64 exec, exec, s[40:41]
	v_or_b32_e32 v122, v122, v130
	v_lshlrev_b64 v[34:35], 1, v[122:123]
	v_or_b32_e32 v34, 0x400, v34
	v_lshl_add_u64 v[36:37], v[114:115], 0, v[34:35]
	global_load_dwordx2 v[38:39], v[36:37], off
	global_load_dwordx2 v[40:41], v[36:37], off offset:16
	global_load_dwordx2 v[42:43], v[36:37], off offset:32
	global_load_dwordx2 v[44:45], v[36:37], off offset:48
	global_load_dwordx2 v[46:47], v[36:37], off offset:64
	global_load_dwordx2 v[50:51], v[36:37], off offset:80
	ds_bpermute_b32 v33, v223, v32
	global_load_dwordx2 v[48:49], v[36:37], off offset:96
	v_lshl_add_u64 v[34:35], v[116:117], 0, v[34:35]
	s_waitcnt lgkmcnt(0)
	v_add_f32_e32 v52, v32, v33
	global_load_dwordx2 v[32:33], v[36:37], off offset:112
	v_div_scale_f32 v53, s[6:7], v52, v52, 1.0
	v_rcp_f32_e32 v54, v53
	v_div_scale_f32 v36, vcc, 1.0, v52, 1.0
	v_fma_f32 v37, -v53, v54, 1.0
	v_fmac_f32_e32 v54, v37, v54
	v_mul_f32_e32 v37, v36, v54
	v_fma_f32 v55, -v53, v37, v36
	v_fmac_f32_e32 v37, v55, v54
	v_fma_f32 v36, -v53, v37, v36
	v_div_fmas_f32 v36, v36, v54, v37
	v_div_fixup_f32 v36, v36, v52, 1.0
	v_pk_mul_f32 v[16:17], v[16:17], v[36:37] op_sel_hi:[1,0]
	v_pk_mul_f32 v[18:19], v[18:19], v[36:37] op_sel_hi:[1,0]
	v_pk_mul_f32 v[0:1], v[0:1], v[36:37] op_sel_hi:[1,0]
	v_pk_mul_f32 v[2:3], v[2:3], v[36:37] op_sel_hi:[1,0]
	v_pk_mul_f32 v[20:21], v[20:21], v[36:37] op_sel_hi:[1,0]
	v_pk_mul_f32 v[22:23], v[22:23], v[36:37] op_sel_hi:[1,0]
	v_pk_mul_f32 v[24:25], v[24:25], v[36:37] op_sel_hi:[1,0]
	v_pk_mul_f32 v[26:27], v[26:27], v[36:37] op_sel_hi:[1,0]
	v_pk_mul_f32 v[28:29], v[28:29], v[36:37] op_sel_hi:[1,0]
	v_pk_mul_f32 v[30:31], v[30:31], v[36:37] op_sel_hi:[1,0]
	v_pk_mul_f32 v[4:5], v[4:5], v[36:37] op_sel_hi:[1,0]
	s_waitcnt vmcnt(7)
	v_lshlrev_b32_e32 v52, 16, v38
	v_and_b32_e32 v53, 0xffff0000, v38
	v_lshlrev_b32_e32 v38, 16, v39
	v_and_b32_e32 v39, 0xffff0000, v39
	s_waitcnt vmcnt(3)
	v_lshlrev_b32_e32 v60, 16, v46
	v_and_b32_e32 v61, 0xffff0000, v46
	v_lshlrev_b32_e32 v46, 16, v47
	v_and_b32_e32 v47, 0xffff0000, v47
	v_lshlrev_b32_e32 v54, 16, v40
	v_and_b32_e32 v55, 0xffff0000, v40
	v_lshlrev_b32_e32 v40, 16, v41
	v_and_b32_e32 v41, 0xffff0000, v41
	v_lshlrev_b32_e32 v56, 16, v42
	v_and_b32_e32 v57, 0xffff0000, v42
	v_lshlrev_b32_e32 v42, 16, v43
	v_and_b32_e32 v43, 0xffff0000, v43
	v_lshlrev_b32_e32 v58, 16, v44
	v_and_b32_e32 v59, 0xffff0000, v44
	v_lshlrev_b32_e32 v44, 16, v45
	v_and_b32_e32 v45, 0xffff0000, v45
	v_pk_mul_f32 v[16:17], v[16:17], v[52:53]
	v_pk_mul_f32 v[18:19], v[18:19], v[38:39]
	v_pk_mul_f32 v[0:1], v[0:1], v[60:61]
	v_pk_mul_f32 v[2:3], v[2:3], v[46:47]
	v_pk_mul_f32 v[20:21], v[20:21], v[54:55]
	v_pk_mul_f32 v[22:23], v[22:23], v[40:41]
	v_pk_mul_f32 v[24:25], v[24:25], v[56:57]
	v_pk_mul_f32 v[26:27], v[26:27], v[42:43]
	v_pk_mul_f32 v[28:29], v[28:29], v[58:59]
	v_pk_mul_f32 v[30:31], v[30:31], v[44:45]
	v_cvt_pk_bf16_f32 v16, v16, v17
	v_cvt_pk_bf16_f32 v17, v18, v19
	v_cvt_pk_bf16_f32 v0, v0, v1
	v_cvt_pk_bf16_f32 v1, v2, v3
	s_waitcnt vmcnt(2)
	v_lshlrev_b32_e32 v62, 16, v50
	v_and_b32_e32 v63, 0xffff0000, v50
	v_cvt_pk_bf16_f32 v18, v20, v21
	v_cvt_pk_bf16_f32 v19, v22, v23
	v_cvt_pk_bf16_f32 v20, v24, v25
	v_cvt_pk_bf16_f32 v21, v26, v27
	v_cvt_pk_bf16_f32 v22, v28, v29
	v_cvt_pk_bf16_f32 v23, v30, v31
	global_store_dwordx2 v[34:35], v[16:17], off
	global_store_dwordx2 v[34:35], v[18:19], off offset:16
	global_store_dwordx2 v[34:35], v[20:21], off offset:32
	global_store_dwordx2 v[34:35], v[22:23], off offset:48
	global_store_dwordx2 v[34:35], v[0:1], off offset:64
	v_lshlrev_b32_e32 v0, 16, v51
	v_and_b32_e32 v1, 0xffff0000, v51
	v_pk_mul_f32 v[2:3], v[6:7], v[36:37] op_sel_hi:[1,0]
	v_pk_mul_f32 v[4:5], v[4:5], v[62:63]
	v_pk_mul_f32 v[0:1], v[2:3], v[0:1]
	v_cvt_pk_bf16_f32 v2, v4, v5
	v_cvt_pk_bf16_f32 v3, v0, v1
	global_store_dwordx2 v[34:35], v[2:3], off offset:80
	s_waitcnt vmcnt(7)
	v_lshlrev_b32_e32 v0, 16, v48
	v_and_b32_e32 v1, 0xffff0000, v48
	v_pk_mul_f32 v[2:3], v[8:9], v[36:37] op_sel_hi:[1,0]
	v_pk_mul_f32 v[4:5], v[10:11], v[36:37] op_sel_hi:[1,0]
	v_pk_mul_f32 v[0:1], v[2:3], v[0:1]
	v_lshlrev_b32_e32 v2, 16, v49
	v_and_b32_e32 v3, 0xffff0000, v49
	v_pk_mul_f32 v[2:3], v[4:5], v[2:3]
	v_cvt_pk_bf16_f32 v0, v0, v1
	v_cvt_pk_bf16_f32 v1, v2, v3
	s_waitcnt vmcnt(6)
	v_and_b32_e32 v3, 0xffff0000, v32
	v_lshlrev_b32_e32 v2, 16, v32
	v_pk_mul_f32 v[4:5], v[12:13], v[36:37] op_sel_hi:[1,0]
	global_store_dwordx2 v[34:35], v[0:1], off offset:96
	v_lshlrev_b32_e32 v0, 16, v33
	v_pk_mul_f32 v[2:3], v[4:5], v[2:3]
	v_and_b32_e32 v1, 0xffff0000, v33
	v_pk_mul_f32 v[4:5], v[14:15], v[36:37] op_sel_hi:[1,0]
	v_cvt_pk_bf16_f32 v2, v2, v3
	v_pk_mul_f32 v[0:1], v[4:5], v[0:1]
	s_nop 0
	v_cvt_pk_bf16_f32 v3, v0, v1
	global_store_dwordx2 v[34:35], v[2:3], off offset:112

.LBB0_390:
	s_or_b64 exec, exec, s[8:9]
	v_add_u32_e32 v10, v5, v142
	v_ashrrev_i32_e32 v11, 31, v10
	v_and_b32_e32 v1, 7, v1
	v_lshlrev_b64 v[122:123], 10, v[10:11]
	v_lshl_add_u64 v[10:11], s[16:17], 0, v[122:123]
	v_lshlrev_b32_e32 v112, 7, v1
	v_lshl_add_u64 v[10:11], v[10:11], 0, v[112:113]
	v_mov_b32_e32 v119, v113
	v_lshl_add_u64 v[10:11], v[10:11], 0, v[118:119]
	v_ashrrev_i32_e32 v7, 31, v6
	global_load_dwordx4 v[64:67], v[10:11], off
	global_load_dwordx4 v[68:71], v[10:11], off offset:32
	global_load_dwordx4 v[72:75], v[10:11], off offset:64
	global_load_dwordx4 v[76:79], v[10:11], off offset:96
	v_lshlrev_b64 v[10:11], 19, v[6:7]
	v_lshl_or_b32 v6, v6, 3, v1
	v_lshl_add_u64 v[10:11], s[20:21], 0, v[10:11]
	v_ashrrev_i32_e32 v7, 31, v6
	v_ashrrev_i32_e32 v5, 31, v4
	v_lshl_add_u64 v[124:125], v[10:11], 0, v[112:113]
	v_lshlrev_b64 v[10:11], 16, v[6:7]
	v_lshlrev_b64 v[4:5], 10, v[4:5]
	v_lshl_add_u64 v[126:127], s[26:27], 0, v[10:11]
	v_lshl_add_u64 v[10:11], s[18:19], 0, v[4:5]
	v_mov_b32_e32 v3, v131
	v_lshl_add_u64 v[10:11], v[10:11], 0, v[112:113]
	v_lshlrev_b64 v[12:13], 15, v[6:7]
	v_lshl_add_u64 v[128:129], s[30:31], 0, v[12:13]
	v_lshlrev_b32_e32 v16, 4, v3
	v_cndmask_b32_e32 v11, v125, v11, vcc
	v_cndmask_b32_e32 v10, v124, v10, vcc
	v_and_b32_e32 v14, 0x70, v16
	v_mov_b32_e32 v15, v113
	v_cndmask_b32_e32 v13, v127, v129, vcc
	v_cndmask_b32_e32 v12, v126, v128, vcc
	v_lshl_add_u64 v[10:11], v[10:11], 0, v[14:15]
	v_and_b32_e32 v14, 48, v16
	v_lshl_add_u64 v[12:13], v[12:13], 0, v[14:15]
	v_ashrrev_i32_e32 v14, 3, v3
	v_ashrrev_i32_e32 v15, 31, v14
	v_lshlrev_b64 v[14:15], 10, v[14:15]
	v_lshl_add_u64 v[14:15], v[10:11], 0, v[14:15]
	global_load_dwordx4 v[80:83], v[14:15], off
	v_ashrrev_i32_e32 v14, 2, v3
	v_ashrrev_i32_e32 v15, 31, v14
	v_lshlrev_b64 v[14:15], v2, v[14:15]
	v_lshl_add_u64 v[14:15], v[14:15], 1, v[12:13]
	v_add_u32_e32 v16, 64, v3
	global_load_dwordx4 v[84:87], v[14:15], off
	v_ashrrev_i32_e32 v14, 3, v16
	v_ashrrev_i32_e32 v15, 31, v14
	v_lshlrev_b64 v[14:15], 10, v[14:15]
	v_lshl_add_u64 v[14:15], v[10:11], 0, v[14:15]
	global_load_dwordx4 v[88:91], v[14:15], off
	v_ashrrev_i32_e32 v14, 2, v16
	v_ashrrev_i32_e32 v15, 31, v14
	v_lshlrev_b64 v[14:15], v2, v[14:15]
	v_lshl_add_u64 v[14:15], v[14:15], 1, v[12:13]
	v_add_u32_e32 v16, 0x80, v3
	global_load_dwordx4 v[92:95], v[14:15], off
	v_ashrrev_i32_e32 v14, 3, v16
	v_ashrrev_i32_e32 v15, 31, v14
	v_lshlrev_b64 v[14:15], 10, v[14:15]
	v_lshl_add_u64 v[14:15], v[10:11], 0, v[14:15]
	global_load_dwordx4 v[96:99], v[14:15], off
	v_ashrrev_i32_e32 v14, 2, v16
	v_ashrrev_i32_e32 v15, 31, v14
	v_lshlrev_b64 v[14:15], v2, v[14:15]
	v_lshl_add_u64 v[14:15], v[14:15], 1, v[12:13]
	v_add_u32_e32 v3, 0xc0, v3
	global_load_dwordx4 v[100:103], v[14:15], off
	v_ashrrev_i32_e32 v14, 3, v3
	v_ashrrev_i32_e32 v15, 31, v14
	v_lshlrev_b64 v[14:15], 10, v[14:15]
	v_lshl_add_u64 v[10:11], v[10:11], 0, v[14:15]
	global_load_dwordx4 v[104:107], v[10:11], off
	v_ashrrev_i32_e32 v10, 2, v3
	v_ashrrev_i32_e32 v11, 31, v10
	v_lshlrev_b64 v[2:3], v2, v[10:11]
	v_lshl_add_u64 v[2:3], v[2:3], 1, v[12:13]
	global_load_dwordx4 v[108:111], v[2:3], off
	v_lshlrev_b32_e32 v130, 6, v1
	v_mul_u32_u24_e32 v1, 0x1d1, v1
	v_lshlrev_b32_e32 v2, 2, v1
	v_sub_u32_e64 v1, v8, 4 clamp
	v_min_u32_e32 v119, 56, v1
	v_ashrrev_i32_e32 v1, 31, v0
	v_lshlrev_b64 v[0:1], 10, v[0:1]
	v_lshl_add_u64 v[0:1], s[18:19], 0, v[0:1]
	v_lshl_add_u64 v[134:135], v[0:1], 0, v[112:113]
	v_lshlrev_b64 v[0:1], 19, v[6:7]
	v_or_b32_e32 v151, v9, v142
	v_lshl_add_u64 v[136:137], s[28:29], 0, v[0:1]
	v_sub_u32_e64 v0, v151, 8 clamp
	v_mov_b32_e32 v3, v113
	v_min_u32_e32 v153, 48, v0
	v_or_b32_e32 v4, v4, v112
	v_mov_b32_e32 v155, 0
	v_lshl_add_u64 v[132:133], s[14:15], 0, v[2:3]
	v_sub_u32_e32 v152, v119, v8
	v_add_u32_e32 v154, 16, v153
	v_lshl_add_u64 v[138:139], s[34:35], 0, v[4:5]
	v_mov_b32_e32 v156, 0xff800000
	s_mov_b32 s65, 0
	s_mov_b32 s63, 32
	s_mov_b64 s[40:41], 0
	s_xor_b64 s[42:43], vcc, -1
	v_mov_b32_e32 v0, 0
	v_mov_b32_e32 v1, v155
	v_mov_b32_e32 v2, v155
	v_mov_b32_e32 v3, v155
	v_mov_b32_e32 v4, v155
	v_mov_b32_e32 v5, v155
	v_mov_b32_e32 v6, v155
	v_mov_b32_e32 v7, v155
	v_mov_b32_e32 v8, v155
	v_mov_b32_e32 v9, v155
	v_mov_b32_e32 v10, v155
	v_mov_b32_e32 v11, v155
	v_mov_b32_e32 v12, v155
	v_mov_b32_e32 v13, v155
	v_mov_b32_e32 v14, v155
	v_mov_b32_e32 v15, v155
	v_mov_b32_e32 v16, 0
	v_mov_b32_e32 v17, v155
	v_mov_b32_e32 v18, v155
	v_mov_b32_e32 v19, v155
	v_mov_b32_e32 v20, v155
	v_mov_b32_e32 v21, v155
	v_mov_b32_e32 v22, v155
	v_mov_b32_e32 v23, v155
	v_mov_b32_e32 v24, v155
	v_mov_b32_e32 v25, v155
	v_mov_b32_e32 v26, v155
	v_mov_b32_e32 v27, v155
	v_mov_b32_e32 v28, v155
	v_mov_b32_e32 v29, v155
	v_mov_b32_e32 v30, v155
	v_mov_b32_e32 v31, v155
	v_lshlrev_b32_e32 v222, 4, v131
	v_and_b32_e32 v220, 0x70, v222
	v_and_b32_e32 v221, 48, v222
	v_lshrrev_b32_e32 v222, 3, v131
	v_mad_u32_u24 v220, v222, s48, v220
	v_add_u32_e32 v220, v143, v220
	v_lshrrev_b32_e32 v222, 2, v131
	v_mad_u32_u24 v221, v222, s61, v221
	v_add_u32_e32 v221, v143, v221
	v_and_b32_e32 v226, 7, v131
	v_lshrrev_b32_e32 v227, 3, v131
	v_lshlrev_b32_e32 v226, 4, v226
	v_lshl_add_u32 v226, v227, 10, v226
	v_and_b32_e32 v227, 3, v131
	v_lshlrev_b32_e32 v227, 4, v227
	v_lshrrev_b32_e32 v228, 2, v131
	v_xor_b32_e32 v223, 32, v149
	v_lshlrev_b32_e32 v223, 2, v223
	v_add_u32_e32 v224, 0x1000, v146
	v_add_u32_e32 v225, 0x1800, v146
	s_branch .LBB0_393
.LBB0_392:
	s_setprio 1
	s_or_b64 exec, exec, s[44:45]
	s_nop 8
	v_max_f32_e32 v48, v33, v33
	v_max_f32_e32 v49, v32, v32
	v_max_f32_e32 v48, v49, v48
	v_max3_f32 v48, v48, v34, v35
	v_max3_f32 v48, v48, v36, v37
	v_max3_f32 v48, v48, v38, v39
	v_max3_f32 v48, v48, v40, v41
	v_max3_f32 v48, v48, v42, v43
	v_max3_f32 v48, v48, v44, v45
	v_max3_f32 v49, v48, v46, v47
	s_add_i32 s63, s63, 32
	ds_bpermute_b32 v50, v223, v49
	v_cmp_eq_u32_e32 vcc, s64, v150
	v_lshl_add_u64 v[138:139], v[138:139], 0, s[38:39]
	s_or_b64 s[40:41], vcc, s[40:41]
	s_mov_b32 s65, s64
	s_waitcnt lgkmcnt(0)
	v_max3_f32 v49, v156, v49, v50
	v_sub_f32_e32 v32, v32, v49
	v_exp_f32_e32 v50, v32
	v_sub_f32_e32 v32, v33, v49
	v_exp_f32_e32 v51, v32
	v_sub_f32_e32 v34, v34, v49
	v_exp_f32_e32 v52, v34
	v_sub_f32_e32 v34, v35, v49
	v_exp_f32_e32 v53, v34
	v_sub_f32_e32 v34, v36, v49
	v_add_f32_e32 v33, 0, v50
	v_exp_f32_e32 v54, v34
	v_sub_f32_e32 v34, v37, v49
	v_add_f32_e32 v33, v51, v33
	v_exp_f32_e32 v55, v34
	v_sub_f32_e32 v34, v38, v49
	v_add_f32_e32 v33, v52, v33
	v_exp_f32_e32 v56, v34
	v_sub_f32_e32 v34, v39, v49
	v_add_f32_e32 v33, v53, v33
	v_exp_f32_e32 v39, v34
	v_sub_f32_e32 v34, v40, v49
	v_add_f32_e32 v33, v54, v33
	v_exp_f32_e32 v57, v34
	v_sub_f32_e32 v34, v41, v49
	v_add_f32_e32 v33, v55, v33
	v_exp_f32_e32 v58, v34
	v_add_f32_e32 v33, v56, v33
	v_add_f32_e32 v33, v39, v33
	v_add_f32_e32 v33, v57, v33
	v_add_f32_e32 v59, v58, v33
	v_sub_f32_e32 v33, v42, v49
	v_exp_f32_e32 v60, v33
	v_sub_f32_e32 v33, v43, v49
	v_sub_f32_e32 v32, v156, v49
	v_exp_f32_e32 v61, v33
	v_sub_f32_e32 v33, v44, v49
	v_exp_f32_e32 v62, v33
	v_sub_f32_e32 v33, v45, v49
	v_exp_f32_e32 v44, v32
	v_sub_f32_e32 v32, v46, v49
	v_cvt_pk_bf16_f32 v36, v50, v51
	v_exp_f32_e32 v45, v33
	v_exp_f32_e32 v46, v32
	ds_read2_b64 v[32:35], v224 offset0:64 offset1:66
	ds_read2_b64 v[40:43], v225 offset0:128 offset1:130
	v_pk_mul_f32 v[30:31], v[30:31], v[44:45] op_sel_hi:[1,0]
	v_pk_mul_f32 v[28:29], v[28:29], v[44:45] op_sel_hi:[1,0]
	v_pk_mul_f32 v[26:27], v[26:27], v[44:45] op_sel_hi:[1,0]
	v_pk_mul_f32 v[24:25], v[24:25], v[44:45] op_sel_hi:[1,0]
	v_pk_mul_f32 v[22:23], v[22:23], v[44:45] op_sel_hi:[1,0]
	v_pk_mul_f32 v[20:21], v[20:21], v[44:45] op_sel_hi:[1,0]
	v_pk_mul_f32 v[18:19], v[18:19], v[44:45] op_sel_hi:[1,0]
	v_pk_mul_f32 v[16:17], v[16:17], v[44:45] op_sel_hi:[1,0]
	v_pk_mul_f32 v[14:15], v[14:15], v[44:45] op_sel_hi:[1,0]
	v_pk_mul_f32 v[12:13], v[12:13], v[44:45] op_sel_hi:[1,0]
	v_cvt_pk_bf16_f32 v37, v52, v53
	v_cvt_pk_bf16_f32 v38, v54, v55
	v_cvt_pk_bf16_f32 v39, v56, v39
	v_pk_mul_f32 v[10:11], v[10:11], v[44:45] op_sel_hi:[1,0]
	v_pk_mul_f32 v[8:9], v[8:9], v[44:45] op_sel_hi:[1,0]
	v_pk_mul_f32 v[6:7], v[6:7], v[44:45] op_sel_hi:[1,0]
	v_pk_mul_f32 v[4:5], v[4:5], v[44:45] op_sel_hi:[1,0]
	v_pk_mul_f32 v[2:3], v[2:3], v[44:45] op_sel_hi:[1,0]
	v_pk_mul_f32 v[0:1], v[0:1], v[44:45] op_sel_hi:[1,0]
	s_waitcnt lgkmcnt(1)
	v_mfma_f32_32x32x16_bf16 v[16:31], v[32:35], v[36:39], v[16:31]
	ds_read2_b64 v[32:35], v224 offset0:68 offset1:70
	v_mov_b32_e32 v156, v49
	s_waitcnt lgkmcnt(1)
	v_mfma_f32_32x32x16_bf16 v[0:15], v[40:43], v[36:39], v[0:15]
	ds_read2_b64 v[40:43], v225 offset0:132 offset1:134
	v_sub_f32_e32 v36, v47, v49
	v_exp_f32_e32 v47, v36
	v_cvt_pk_bf16_f32 v36, v57, v58
	v_cvt_pk_bf16_f32 v37, v60, v61
	v_cvt_pk_bf16_f32 v38, v62, v45
	v_cvt_pk_bf16_f32 v39, v46, v47
	s_waitcnt lgkmcnt(1)
	s_nop 0
	v_mfma_f32_32x32x16_bf16 v[16:31], v[32:35], v[36:39], v[16:31]
	v_add_f32_e32 v32, v60, v59
	v_add_f32_e32 v32, v61, v32
	v_add_f32_e32 v32, v62, v32
	v_add_f32_e32 v32, v45, v32
	v_add_f32_e32 v32, v46, v32
	v_add_f32_e32 v32, v47, v32
	v_fmac_f32_e32 v32, v155, v44
	s_waitcnt lgkmcnt(0)
	v_mfma_f32_32x32x16_bf16 v[0:15], v[40:43], v[36:39], v[0:15]
	v_mov_b32_e32 v155, v32
	s_andn2_b64 exec, exec, s[40:41]
	s_cbranch_execz .LBB0_376
